# E_OUT epilogue too: x loads pipelined 4 row-groups deep with counted waits; kernarg pointer select made scalar
# speedup vs baseline: 1.0332x; 1.0170x over previous
.LBB0_928:
	s_and_b64 vcc, exec, s[2:3]
	s_cbranch_vccz .LBB0_1042
	s_cmp_gt_i32 s63, 1
	s_mov_b64 s[0:1], -1
	s_cbranch_scc0 .LBB0_951
	s_cmp_gt_i32 s63, 2
	s_cbranch_scc0 .LBB0_948
	v_readlane_b32 s0, v254, 56
	v_readlane_b32 s1, v254, 57
	s_load_dwordx4 s[0:3], s[0:1], 0x0
	v_ashrrev_i32_e32 v149, 31, v148
	v_add_u32_e32 v134, v132, v167
	v_ashrrev_i32_e32 v135, 31, v134
	v_lshlrev_b64 v[250:251], 11, v[148:149]
	v_lshl_add_u64 v[250:251], s[46:47], 0, v[250:251]
	v_lshl_add_u64 v[250:251], v[134:135], 1, v[250:251]
	v_lshl_add_u64 v[252:253], v[148:149], 2, s[50:51]
	v_xor_b32_e32 v132, 16, v230
	v_xor_b32_e32 v133, 32, v230
	v_lshlrev_b32_e32 v132, 2, v132
	v_lshlrev_b32_e32 v133, 2, v133
	s_waitcnt lgkmcnt(0)
	s_cmpk_lt_i32 s81, 0x4000
	s_cselect_b32 s0, s0, s2
	s_cselect_b32 s1, s1, s3
	s_cselect_b32 s6, 0, 0x4000
	v_subrev_u32_e32 v248, s6, v148
	v_ashrrev_i32_e32 v249, 31, v248
	v_lshlrev_b64 v[248:249], 12, v[248:249]
	v_lshl_add_u64 v[248:249], s[0:1], 0, v[248:249]
	v_lshl_add_u64 v[248:249], v[134:135], 2, v[248:249]
	global_load_dwordx4 v[196:199], v[248:249], off nt
	global_load_dwordx4 v[200:203], v[248:249], off offset:16 nt
	global_load_dwordx4 v[204:207], v[248:249], off offset:512 nt
	global_load_dwordx4 v[208:211], v[248:249], off offset:528 nt
	s_mov_b64 s[2:3], 0x10000
	v_lshl_add_u64 v[248:249], v[248:249], 0, s[2:3]
	global_load_dwordx4 v[212:215], v[248:249], off nt
	global_load_dwordx4 v[216:219], v[248:249], off offset:16 nt
	global_load_dwordx4 v[220:223], v[248:249], off offset:512 nt
	global_load_dwordx4 v[224:227], v[248:249], off offset:528 nt
	v_lshl_add_u64 v[248:249], v[248:249], 0, s[2:3]
	global_load_dwordx4 v[232:235], v[248:249], off nt
	global_load_dwordx4 v[236:239], v[248:249], off offset:16 nt
	global_load_dwordx4 v[240:243], v[248:249], off offset:512 nt
	global_load_dwordx4 v[244:247], v[248:249], off offset:528 nt
	v_lshl_add_u64 v[248:249], v[248:249], 0, s[2:3]
	global_load_dwordx4 v[148:151], v[248:249], off nt
	global_load_dwordx4 v[152:155], v[248:249], off offset:16 nt
	global_load_dwordx4 v[156:159], v[248:249], off offset:512 nt
	global_load_dwordx4 v[160:163], v[248:249], off offset:528 nt
	s_mov_b64 s[2:3], 0x50000
	v_lshl_add_u64 v[248:249], v[248:249], 0, s[2:3]
	s_waitcnt vmcnt(12)
	v_pk_add_f32 v[128:129], v[128:129], v[196:197]
	v_pk_add_f32 v[130:131], v[130:131], v[198:199]
	v_pk_add_f32 v[124:125], v[124:125], v[200:201]
	v_pk_add_f32 v[126:127], v[126:127], v[202:203]
	v_pk_add_f32 v[120:121], v[120:121], v[204:205]
	v_pk_add_f32 v[122:123], v[122:123], v[206:207]
	v_pk_add_f32 v[116:117], v[116:117], v[208:209]
	v_pk_add_f32 v[118:119], v[118:119], v[210:211]
	v_mul_f32_e32 v196, v129, v129
	v_mul_f32_e32 v197, v131, v131
	v_fmac_f32_e32 v196, v128, v128
	v_fmac_f32_e32 v197, v130, v130
	v_mul_f32_e32 v198, v125, v125
	v_mul_f32_e32 v199, v127, v127
	v_add_f32_e32 v196, v196, v197
	v_fmac_f32_e32 v198, v124, v124
	v_fmac_f32_e32 v199, v126, v126
	v_cvt_pk_bf16_f32 v128, v128, v129
	v_add_f32_e32 v198, v198, v199
	v_cvt_pk_bf16_f32 v129, v130, v131
	v_add_f32_e32 v196, v196, v198
	v_cvt_pk_bf16_f32 v130, v124, v125
	v_cvt_pk_bf16_f32 v131, v126, v127
	global_store_dwordx4 v[250:251], v[128:131], off
	v_mul_f32_e32 v204, v121, v121
	v_mul_f32_e32 v205, v123, v123
	v_fmac_f32_e32 v204, v120, v120
	v_fmac_f32_e32 v205, v122, v122
	v_mul_f32_e32 v206, v117, v117
	v_mul_f32_e32 v207, v119, v119
	v_add_f32_e32 v204, v204, v205
	v_fmac_f32_e32 v206, v116, v116
	v_fmac_f32_e32 v207, v118, v118
	v_cvt_pk_bf16_f32 v120, v120, v121
	v_add_f32_e32 v206, v206, v207
	v_cvt_pk_bf16_f32 v121, v122, v123
	v_add_f32_e32 v204, v204, v206
	v_cvt_pk_bf16_f32 v122, v116, v117
	v_cvt_pk_bf16_f32 v123, v118, v119
	global_store_dwordx4 v[250:251], v[120:123], off offset:256
	v_add_f32_e32 v124, v196, v204
	global_load_dwordx4 v[196:199], v[248:249], off nt
	global_load_dwordx4 v[200:203], v[248:249], off offset:16 nt
	global_load_dwordx4 v[204:207], v[248:249], off offset:512 nt
	global_load_dwordx4 v[208:211], v[248:249], off offset:528 nt
	s_mov_b64 s[2:3], 0x10000
	v_lshl_add_u64 v[248:249], v[248:249], 0, s[2:3]
	s_mov_b64 s[6:7], 0x8000
	v_lshl_add_u64 v[250:251], v[250:251], 0, s[6:7]
	s_waitcnt vmcnt(14)
	v_pk_add_f32 v[108:109], v[108:109], v[212:213]
	v_pk_add_f32 v[110:111], v[110:111], v[214:215]
	v_pk_add_f32 v[100:101], v[100:101], v[216:217]
	v_pk_add_f32 v[102:103], v[102:103], v[218:219]
	v_pk_add_f32 v[112:113], v[112:113], v[220:221]
	v_pk_add_f32 v[114:115], v[114:115], v[222:223]
	v_pk_add_f32 v[104:105], v[104:105], v[224:225]
	v_pk_add_f32 v[106:107], v[106:107], v[226:227]
	v_mul_f32_e32 v212, v109, v109
	v_mul_f32_e32 v213, v111, v111
	v_fmac_f32_e32 v212, v108, v108
	v_fmac_f32_e32 v213, v110, v110
	v_mul_f32_e32 v214, v101, v101
	v_mul_f32_e32 v215, v103, v103
	v_add_f32_e32 v212, v212, v213
	v_fmac_f32_e32 v214, v100, v100
	v_fmac_f32_e32 v215, v102, v102
	v_cvt_pk_bf16_f32 v108, v108, v109
	v_add_f32_e32 v214, v214, v215
	v_cvt_pk_bf16_f32 v109, v110, v111
	v_add_f32_e32 v212, v212, v214
	v_cvt_pk_bf16_f32 v110, v100, v101
	v_cvt_pk_bf16_f32 v111, v102, v103
	global_store_dwordx4 v[250:251], v[108:111], off
	v_mul_f32_e32 v220, v113, v113
	v_mul_f32_e32 v221, v115, v115
	v_fmac_f32_e32 v220, v112, v112
	v_fmac_f32_e32 v221, v114, v114
	v_mul_f32_e32 v222, v105, v105
	v_mul_f32_e32 v223, v107, v107
	v_add_f32_e32 v220, v220, v221
	v_fmac_f32_e32 v222, v104, v104
	v_fmac_f32_e32 v223, v106, v106
	v_cvt_pk_bf16_f32 v112, v112, v113
	v_add_f32_e32 v222, v222, v223
	v_cvt_pk_bf16_f32 v113, v114, v115
	v_add_f32_e32 v220, v220, v222
	v_cvt_pk_bf16_f32 v114, v104, v105
	v_cvt_pk_bf16_f32 v115, v106, v107
	global_store_dwordx4 v[250:251], v[112:115], off offset:256
	v_add_f32_e32 v100, v212, v220
	global_load_dwordx4 v[212:215], v[248:249], off nt
	global_load_dwordx4 v[216:219], v[248:249], off offset:16 nt
	global_load_dwordx4 v[220:223], v[248:249], off offset:512 nt
	global_load_dwordx4 v[224:227], v[248:249], off offset:528 nt
	v_lshl_add_u64 v[248:249], v[248:249], 0, s[2:3]
	v_lshl_add_u64 v[250:251], v[250:251], 0, s[6:7]
	s_waitcnt vmcnt(16)
	v_pk_add_f32 v[88:89], v[88:89], v[232:233]
	v_pk_add_f32 v[90:91], v[90:91], v[234:235]
	v_pk_add_f32 v[84:85], v[84:85], v[236:237]
	v_pk_add_f32 v[86:87], v[86:87], v[238:239]
	v_pk_add_f32 v[96:97], v[96:97], v[240:241]
	v_pk_add_f32 v[98:99], v[98:99], v[242:243]
	v_pk_add_f32 v[92:93], v[92:93], v[244:245]
	v_pk_add_f32 v[94:95], v[94:95], v[246:247]
	v_mul_f32_e32 v232, v89, v89
	v_mul_f32_e32 v233, v91, v91
	v_fmac_f32_e32 v232, v88, v88
	v_fmac_f32_e32 v233, v90, v90
	v_mul_f32_e32 v234, v85, v85
	v_mul_f32_e32 v235, v87, v87
	v_add_f32_e32 v232, v232, v233
	v_fmac_f32_e32 v234, v84, v84
	v_fmac_f32_e32 v235, v86, v86
	v_cvt_pk_bf16_f32 v88, v88, v89
	v_add_f32_e32 v234, v234, v235
	v_cvt_pk_bf16_f32 v89, v90, v91
	v_add_f32_e32 v232, v232, v234
	v_cvt_pk_bf16_f32 v90, v84, v85
	v_cvt_pk_bf16_f32 v91, v86, v87
	global_store_dwordx4 v[250:251], v[88:91], off
	v_mul_f32_e32 v240, v97, v97
	v_mul_f32_e32 v241, v99, v99
	v_fmac_f32_e32 v240, v96, v96
	v_fmac_f32_e32 v241, v98, v98
	v_mul_f32_e32 v242, v93, v93
	v_mul_f32_e32 v243, v95, v95
	v_add_f32_e32 v240, v240, v241
	v_fmac_f32_e32 v242, v92, v92
	v_fmac_f32_e32 v243, v94, v94
	v_cvt_pk_bf16_f32 v96, v96, v97
	v_add_f32_e32 v242, v242, v243
	v_cvt_pk_bf16_f32 v97, v98, v99
	v_add_f32_e32 v240, v240, v242
	v_cvt_pk_bf16_f32 v98, v92, v93
	v_cvt_pk_bf16_f32 v99, v94, v95
	global_store_dwordx4 v[250:251], v[96:99], off offset:256
	v_add_f32_e32 v84, v232, v240
	global_load_dwordx4 v[232:235], v[248:249], off nt
	global_load_dwordx4 v[236:239], v[248:249], off offset:16 nt
	global_load_dwordx4 v[240:243], v[248:249], off offset:512 nt
	global_load_dwordx4 v[244:247], v[248:249], off offset:528 nt
	v_lshl_add_u64 v[248:249], v[248:249], 0, s[2:3]
	v_lshl_add_u64 v[250:251], v[250:251], 0, s[6:7]
	s_waitcnt vmcnt(18)
	v_pk_add_f32 v[56:57], v[56:57], v[148:149]
	v_pk_add_f32 v[58:59], v[58:59], v[150:151]
	v_pk_add_f32 v[44:45], v[44:45], v[152:153]
	v_pk_add_f32 v[46:47], v[46:47], v[154:155]
	v_pk_add_f32 v[80:81], v[80:81], v[156:157]
	v_pk_add_f32 v[82:83], v[82:83], v[158:159]
	v_pk_add_f32 v[76:77], v[76:77], v[160:161]
	v_pk_add_f32 v[78:79], v[78:79], v[162:163]
	v_mul_f32_e32 v148, v57, v57
	v_mul_f32_e32 v149, v59, v59
	v_fmac_f32_e32 v148, v56, v56
	v_fmac_f32_e32 v149, v58, v58
	v_mul_f32_e32 v150, v45, v45
	v_mul_f32_e32 v151, v47, v47
	v_add_f32_e32 v148, v148, v149
	v_fmac_f32_e32 v150, v44, v44
	v_fmac_f32_e32 v151, v46, v46
	v_cvt_pk_bf16_f32 v56, v56, v57
	v_add_f32_e32 v150, v150, v151
	v_cvt_pk_bf16_f32 v57, v58, v59
	v_add_f32_e32 v148, v148, v150
	v_cvt_pk_bf16_f32 v58, v44, v45
	v_cvt_pk_bf16_f32 v59, v46, v47
	global_store_dwordx4 v[250:251], v[56:59], off
	v_mul_f32_e32 v156, v81, v81
	v_mul_f32_e32 v157, v83, v83
	v_fmac_f32_e32 v156, v80, v80
	v_fmac_f32_e32 v157, v82, v82
	v_mul_f32_e32 v158, v77, v77
	v_mul_f32_e32 v159, v79, v79
	v_add_f32_e32 v156, v156, v157
	v_fmac_f32_e32 v158, v76, v76
	v_fmac_f32_e32 v159, v78, v78
	v_cvt_pk_bf16_f32 v80, v80, v81
	v_add_f32_e32 v158, v158, v159
	v_cvt_pk_bf16_f32 v81, v82, v83
	v_add_f32_e32 v156, v156, v158
	v_cvt_pk_bf16_f32 v82, v76, v77
	v_cvt_pk_bf16_f32 v83, v78, v79
	global_store_dwordx4 v[250:251], v[80:83], off offset:256
	v_add_f32_e32 v44, v148, v156
	global_load_dwordx4 v[148:151], v[248:249], off nt
	global_load_dwordx4 v[152:155], v[248:249], off offset:16 nt
	global_load_dwordx4 v[156:159], v[248:249], off offset:512 nt
	global_load_dwordx4 v[160:163], v[248:249], off offset:528 nt
	s_mov_b64 s[6:7], 0x28000
	v_lshl_add_u64 v[250:251], v[250:251], 0, s[6:7]
	s_waitcnt vmcnt(18)
	v_pk_add_f32 v[64:65], v[64:65], v[196:197]
	v_pk_add_f32 v[66:67], v[66:67], v[198:199]
	v_pk_add_f32 v[60:61], v[60:61], v[200:201]
	v_pk_add_f32 v[62:63], v[62:63], v[202:203]
	v_pk_add_f32 v[72:73], v[72:73], v[204:205]
	v_pk_add_f32 v[74:75], v[74:75], v[206:207]
	v_pk_add_f32 v[68:69], v[68:69], v[208:209]
	v_pk_add_f32 v[70:71], v[70:71], v[210:211]
	v_mul_f32_e32 v196, v65, v65
	v_mul_f32_e32 v197, v67, v67
	v_fmac_f32_e32 v196, v64, v64
	v_fmac_f32_e32 v197, v66, v66
	v_mul_f32_e32 v198, v61, v61
	v_mul_f32_e32 v199, v63, v63
	v_add_f32_e32 v196, v196, v197
	v_fmac_f32_e32 v198, v60, v60
	v_fmac_f32_e32 v199, v62, v62
	v_cvt_pk_bf16_f32 v64, v64, v65
	v_add_f32_e32 v198, v198, v199
	v_cvt_pk_bf16_f32 v65, v66, v67
	v_add_f32_e32 v196, v196, v198
	v_cvt_pk_bf16_f32 v66, v60, v61
	v_cvt_pk_bf16_f32 v67, v62, v63
	global_store_dwordx4 v[250:251], v[64:67], off
	v_mul_f32_e32 v204, v73, v73
	v_mul_f32_e32 v205, v75, v75
	v_fmac_f32_e32 v204, v72, v72
	v_fmac_f32_e32 v205, v74, v74
	v_mul_f32_e32 v206, v69, v69
	v_mul_f32_e32 v207, v71, v71
	v_add_f32_e32 v204, v204, v205
	v_fmac_f32_e32 v206, v68, v68
	v_fmac_f32_e32 v207, v70, v70
	v_cvt_pk_bf16_f32 v72, v72, v73
	v_add_f32_e32 v206, v206, v207
	v_cvt_pk_bf16_f32 v73, v74, v75
	v_add_f32_e32 v204, v204, v206
	v_cvt_pk_bf16_f32 v74, v68, v69
	v_cvt_pk_bf16_f32 v75, v70, v71
	global_store_dwordx4 v[250:251], v[72:75], off offset:256
	v_add_f32_e32 v60, v196, v204
	s_mov_b64 s[6:7], 0x8000
	v_lshl_add_u64 v[250:251], v[250:251], 0, s[6:7]
	s_waitcnt vmcnt(14)
	v_pk_add_f32 v[40:41], v[40:41], v[212:213]
	v_pk_add_f32 v[42:43], v[42:43], v[214:215]
	v_pk_add_f32 v[36:37], v[36:37], v[216:217]
	v_pk_add_f32 v[38:39], v[38:39], v[218:219]
	v_pk_add_f32 v[52:53], v[52:53], v[220:221]
	v_pk_add_f32 v[54:55], v[54:55], v[222:223]
	v_pk_add_f32 v[48:49], v[48:49], v[224:225]
	v_pk_add_f32 v[50:51], v[50:51], v[226:227]
	v_mul_f32_e32 v212, v41, v41
	v_mul_f32_e32 v213, v43, v43
	v_fmac_f32_e32 v212, v40, v40
	v_fmac_f32_e32 v213, v42, v42
	v_mul_f32_e32 v214, v37, v37
	v_mul_f32_e32 v215, v39, v39
	v_add_f32_e32 v212, v212, v213
	v_fmac_f32_e32 v214, v36, v36
	v_fmac_f32_e32 v215, v38, v38
	v_cvt_pk_bf16_f32 v40, v40, v41
	v_add_f32_e32 v214, v214, v215
	v_cvt_pk_bf16_f32 v41, v42, v43
	v_add_f32_e32 v212, v212, v214
	v_cvt_pk_bf16_f32 v42, v36, v37
	v_cvt_pk_bf16_f32 v43, v38, v39
	global_store_dwordx4 v[250:251], v[40:43], off
	v_mul_f32_e32 v220, v53, v53
	v_mul_f32_e32 v221, v55, v55
	v_fmac_f32_e32 v220, v52, v52
	v_fmac_f32_e32 v221, v54, v54
	v_mul_f32_e32 v222, v49, v49
	v_mul_f32_e32 v223, v51, v51
	v_add_f32_e32 v220, v220, v221
	v_fmac_f32_e32 v222, v48, v48
	v_fmac_f32_e32 v223, v50, v50
	v_cvt_pk_bf16_f32 v52, v52, v53
	v_add_f32_e32 v222, v222, v223
	v_cvt_pk_bf16_f32 v53, v54, v55
	v_add_f32_e32 v220, v220, v222
	v_cvt_pk_bf16_f32 v54, v48, v49
	v_cvt_pk_bf16_f32 v55, v50, v51
	global_store_dwordx4 v[250:251], v[52:55], off offset:256
	v_add_f32_e32 v36, v212, v220
	v_lshl_add_u64 v[250:251], v[250:251], 0, s[6:7]
	s_waitcnt vmcnt(10)
	v_pk_add_f32 v[22:23], v[22:23], v[232:233]
	v_pk_add_f32 v[24:25], v[24:25], v[234:235]
	v_pk_add_f32 v[18:19], v[18:19], v[236:237]
	v_pk_add_f32 v[20:21], v[20:21], v[238:239]
	v_pk_add_f32 v[32:33], v[32:33], v[240:241]
	v_pk_add_f32 v[34:35], v[34:35], v[242:243]
	v_pk_add_f32 v[28:29], v[28:29], v[244:245]
	v_pk_add_f32 v[30:31], v[30:31], v[246:247]
	v_mul_f32_e32 v232, v23, v23
	v_mul_f32_e32 v233, v25, v25
	v_fmac_f32_e32 v232, v22, v22
	v_fmac_f32_e32 v233, v24, v24
	v_mul_f32_e32 v234, v19, v19
	v_mul_f32_e32 v235, v21, v21
	v_add_f32_e32 v232, v232, v233
	v_fmac_f32_e32 v234, v18, v18
	v_fmac_f32_e32 v235, v20, v20
	v_cvt_pk_bf16_f32 v22, v22, v23
	v_add_f32_e32 v234, v234, v235
	v_cvt_pk_bf16_f32 v23, v24, v25
	v_add_f32_e32 v232, v232, v234
	v_cvt_pk_bf16_f32 v24, v18, v19
	v_cvt_pk_bf16_f32 v25, v20, v21
	global_store_dwordx4 v[250:251], v[22:25], off
	v_mul_f32_e32 v240, v33, v33
	v_mul_f32_e32 v241, v35, v35
	v_fmac_f32_e32 v240, v32, v32
	v_fmac_f32_e32 v241, v34, v34
	v_mul_f32_e32 v242, v29, v29
	v_mul_f32_e32 v243, v31, v31
	v_add_f32_e32 v240, v240, v241
	v_fmac_f32_e32 v242, v28, v28
	v_fmac_f32_e32 v243, v30, v30
	v_cvt_pk_bf16_f32 v32, v32, v33
	v_add_f32_e32 v242, v242, v243
	v_cvt_pk_bf16_f32 v33, v34, v35
	v_add_f32_e32 v240, v240, v242
	v_cvt_pk_bf16_f32 v34, v28, v29
	v_cvt_pk_bf16_f32 v35, v30, v31
	global_store_dwordx4 v[250:251], v[32:35], off offset:256
	v_add_f32_e32 v18, v232, v240
	v_lshl_add_u64 v[250:251], v[250:251], 0, s[6:7]
	s_waitcnt vmcnt(6)
	v_pk_add_f32 v[6:7], v[6:7], v[148:149]
	v_pk_add_f32 v[8:9], v[8:9], v[150:151]
	v_pk_add_f32 v[2:3], v[2:3], v[152:153]
	v_pk_add_f32 v[4:5], v[4:5], v[154:155]
	v_pk_add_f32 v[14:15], v[14:15], v[156:157]
	v_pk_add_f32 v[16:17], v[16:17], v[158:159]
	v_pk_add_f32 v[10:11], v[10:11], v[160:161]
	v_pk_add_f32 v[12:13], v[12:13], v[162:163]
	v_mul_f32_e32 v148, v7, v7
	v_mul_f32_e32 v149, v9, v9
	v_fmac_f32_e32 v148, v6, v6
	v_fmac_f32_e32 v149, v8, v8
	v_mul_f32_e32 v150, v3, v3
	v_mul_f32_e32 v151, v5, v5
	v_add_f32_e32 v148, v148, v149
	v_fmac_f32_e32 v150, v2, v2
	v_fmac_f32_e32 v151, v4, v4
	v_cvt_pk_bf16_f32 v6, v6, v7
	v_add_f32_e32 v150, v150, v151
	v_cvt_pk_bf16_f32 v7, v8, v9
	v_add_f32_e32 v148, v148, v150
	v_cvt_pk_bf16_f32 v8, v2, v3
	v_cvt_pk_bf16_f32 v9, v4, v5
	global_store_dwordx4 v[250:251], v[6:9], off
	v_mul_f32_e32 v156, v15, v15
	v_mul_f32_e32 v157, v17, v17
	v_fmac_f32_e32 v156, v14, v14
	v_fmac_f32_e32 v157, v16, v16
	v_mul_f32_e32 v158, v11, v11
	v_mul_f32_e32 v159, v13, v13
	v_add_f32_e32 v156, v156, v157
	v_fmac_f32_e32 v158, v10, v10
	v_fmac_f32_e32 v159, v12, v12
	v_cvt_pk_bf16_f32 v14, v14, v15
	v_add_f32_e32 v158, v158, v159
	v_cvt_pk_bf16_f32 v15, v16, v17
	v_add_f32_e32 v156, v156, v158
	v_cvt_pk_bf16_f32 v16, v10, v11
	v_cvt_pk_bf16_f32 v17, v12, v13
	global_store_dwordx4 v[250:251], v[14:17], off offset:256
	v_add_f32_e32 v2, v148, v156
	ds_bpermute_b32 v125, v132, v124
	ds_bpermute_b32 v101, v132, v100
	ds_bpermute_b32 v85, v132, v84
	ds_bpermute_b32 v45, v132, v44
	ds_bpermute_b32 v61, v132, v60
	ds_bpermute_b32 v37, v132, v36
	ds_bpermute_b32 v19, v132, v18
	ds_bpermute_b32 v3, v132, v2
	s_waitcnt lgkmcnt(0)
	v_add_f32_e32 v124, v124, v125
	v_add_f32_e32 v100, v100, v101
	v_add_f32_e32 v84, v84, v85
	v_add_f32_e32 v44, v44, v45
	v_add_f32_e32 v60, v60, v61
	v_add_f32_e32 v36, v36, v37
	v_add_f32_e32 v18, v18, v19
	v_add_f32_e32 v2, v2, v3
	ds_bpermute_b32 v125, v133, v124
	ds_bpermute_b32 v101, v133, v100
	ds_bpermute_b32 v85, v133, v84
	ds_bpermute_b32 v45, v133, v44
	ds_bpermute_b32 v61, v133, v60
	ds_bpermute_b32 v37, v133, v36
	ds_bpermute_b32 v19, v133, v18
	ds_bpermute_b32 v3, v133, v2
	s_and_saveexec_b64 s[0:1], s[4:5]
	s_cbranch_execz .LBB0_947
	s_waitcnt lgkmcnt(0)
	v_add_f32_e32 v124, v124, v125
	v_add_f32_e32 v100, v100, v101
	v_add_f32_e32 v84, v84, v85
	v_add_f32_e32 v44, v44, v45
	v_add_f32_e32 v60, v60, v61
	v_add_f32_e32 v36, v36, v37
	v_add_f32_e32 v18, v18, v19
	v_add_f32_e32 v2, v2, v3
	global_atomic_add_f32 v[252:253], v124, off
	global_atomic_add_f32 v[252:253], v100, off offset:64
	global_atomic_add_f32 v[252:253], v84, off offset:128
	global_atomic_add_f32 v[252:253], v44, off offset:192
	global_atomic_add_f32 v[252:253], v60, off offset:512
	global_atomic_add_f32 v[252:253], v36, off offset:576
	global_atomic_add_f32 v[252:253], v18, off offset:640
	global_atomic_add_f32 v[252:253], v2, off offset:704
